# v48 + attention K/V staging waits counted (vmcnt 3/2 when the next tile's loads are in flight) so staged tiles really get two tile steps to land
# speedup vs baseline: 1.0010x; 1.0010x over previous
.LBB0_684:
	s_mov_b32 s80, s76
	s_cmp_lt_i32 s77, 0
	v_add_u32_e32 v131, 0x13600, v133
	s_cbranch_scc1 .LBB0_686
	v_add_u32_e32 v50, s87, v127
	s_cmp_lt_i32 s80, 0
	s_cbranch_scc1 .Lvm_slow_0
	s_waitcnt vmcnt(3)
	ds_write_b128 v131, v[110:113]
	s_waitcnt vmcnt(2)
	ds_write2_b64 v50, v[106:107], v[108:109] offset1:1
	s_branch .Lvm_done_0
.Lvm_slow_0:
	s_waitcnt vmcnt(1)
	ds_write_b128 v131, v[110:113]
	s_waitcnt vmcnt(0)
	ds_write2_b64 v50, v[106:107], v[108:109] offset1:1
.Lvm_done_0:
.LBB0_686:
	s_flbit_i32_b64 s0, s[96:97]
	s_xor_b32 s72, s0, 63
	s_cmp_lg_u64 s[96:97], 0
	s_cselect_b32 s78, s72, -1
	s_cmp_lt_i32 s78, 0
	s_cbranch_scc1 .LBB0_688
	v_lshl_add_u32 v50, s78, 6, v116
	v_mad_i64_i32 v[50:51], s[0:1], v50, s85, v[120:121]
	s_lshl_b32 s82, s78, 7
	v_lshl_add_u64 v[52:53], v[124:125], 0, s[82:83]
	global_load_dwordx4 v[110:113], v[50:51], off offset:512
	global_load_dwordx4 v[106:109], v[52:53], off

.LBB0_695:
	s_cmp_lt_i32 s77, 0
	s_mov_b64 s[0:1], -1
	s_barrier
	s_cbranch_scc1 .LBB0_682
	s_add_i32 s0, s87, 0x2200
	s_cmpk_lg_i32 s87, 0x4400
	s_cselect_b32 s86, s0, 0
	s_cmp_lt_i32 s80, 0
	s_cbranch_scc1 .LBB0_698
	v_add_u32_e32 v50, s86, v127
	s_cmp_lt_i32 s78, 0
	s_cbranch_scc1 .Lvm_slow_1
	s_waitcnt vmcnt(3)
	ds_write_b128 v126, v[98:101]
	s_waitcnt vmcnt(2)
	ds_write2_b64 v50, v[102:103], v[104:105] offset1:1
	s_branch .Lvm_done_1
.Lvm_slow_1:
	s_waitcnt vmcnt(1)
	ds_write_b128 v126, v[98:101]
	s_waitcnt vmcnt(0)
	ds_write2_b64 v50, v[102:103], v[104:105] offset1:1
.Lvm_done_1:
.LBB0_698:
	s_lshl_b64 s[0:1], 1, s72
	s_andn2_b64 s[72:73], s[96:97], s[0:1]
	s_flbit_i32_b64 s0, s[72:73]
	s_xor_b32 s81, s0, 63
	s_cmp_lg_u64 s[72:73], 0
	s_cselect_b32 s76, s81, -1
	s_cmp_lt_i32 s76, 0
	s_cbranch_scc1 .LBB0_700
	v_lshl_add_u32 v50, s76, 6, v116
	v_mad_i64_i32 v[50:51], s[0:1], v50, s85, v[120:121]
	s_lshl_b32 s82, s76, 7
	v_lshl_add_u64 v[52:53], v[124:125], 0, s[82:83]
	global_load_dwordx4 v[98:101], v[50:51], off offset:512
	global_load_dwordx4 v[102:105], v[52:53], off

.LBB0_719:
	s_cmp_lt_i32 s11, 0
	s_mov_b32 s7, s12
	s_cbranch_scc1 .LBB0_721
	v_add_u32_e32 v0, s10, v127
	s_cmp_lt_i32 s7, 0
	s_cbranch_scc1 .Lvm_slow_2
	s_waitcnt vmcnt(3)
	ds_write_b128 v131, v[110:113]
	s_waitcnt vmcnt(2)
	ds_write2_b64 v0, v[106:107], v[108:109] offset1:1
	s_branch .Lvm_done_2
.Lvm_slow_2:
	s_waitcnt vmcnt(1)
	ds_write_b128 v131, v[110:113]
	s_waitcnt vmcnt(0)
	ds_write2_b64 v0, v[106:107], v[108:109] offset1:1
.Lvm_done_2:
.LBB0_721:
	s_flbit_i32_b64 s0, s[2:3]
	s_xor_b32 s4, s0, 63
	s_cmp_lg_u64 s[2:3], 0
	s_cselect_b32 s8, s4, -1
	s_cmp_lt_i32 s8, 0
	s_cbranch_scc1 .LBB0_723
	v_lshl_add_u32 v0, s8, 6, v116
	v_mad_i64_i32 v[50:51], s[0:1], v0, s85, v[120:121]
	s_lshl_b32 s82, s8, 7
	v_lshl_add_u64 v[52:53], v[122:123], 0, s[82:83]
	global_load_dwordx4 v[110:113], v[50:51], off offset:1024
	global_load_dwordx4 v[106:109], v[52:53], off

.LBB0_730:
	s_cmp_lt_i32 s11, 0
	s_mov_b64 s[0:1], -1
	s_barrier
	s_cbranch_scc1 .LBB0_717
	s_add_i32 s0, s10, 0x2200
	s_cmpk_lg_i32 s10, 0x4400
	s_cselect_b32 s9, s0, 0
	s_cmp_lt_i32 s7, 0
	s_cbranch_scc1 .LBB0_733
	v_add_u32_e32 v50, s9, v127
	s_cmp_lt_i32 s8, 0
	s_cbranch_scc1 .Lvm_slow_3
	s_waitcnt vmcnt(3)
	ds_write_b128 v126, v[98:101]
	s_waitcnt vmcnt(2)
	ds_write2_b64 v50, v[102:103], v[104:105] offset1:1
	s_branch .Lvm_done_3

.Lvm_done_3:
.LBB0_733:
	s_lshl_b64 s[0:1], 1, s4
	s_andn2_b64 s[4:5], s[2:3], s[0:1]
	s_flbit_i32_b64 s0, s[4:5]
	s_xor_b32 s13, s0, 63
	s_cmp_lg_u64 s[4:5], 0
	s_cselect_b32 s12, s13, -1
	s_cmp_lt_i32 s12, 0
	s_cbranch_scc1 .LBB0_735
	v_lshl_add_u32 v50, s12, 6, v116
	v_mad_i64_i32 v[50:51], s[0:1], v50, s85, v[120:121]
	s_lshl_b32 s82, s12, 7
	v_lshl_add_u64 v[52:53], v[122:123], 0, s[82:83]
	global_load_dwordx4 v[98:101], v[50:51], off offset:1024
	global_load_dwordx4 v[102:105], v[52:53], off
